# stack3 + the six hot loop headers placed at 4 bytes past a 64-byte boundary (placement comparison)
# speedup vs baseline: 1.0205x; 1.0043x over previous
; template <class Epi, class Sched, bool ALIGN_EPI = false, bool SP2 = false>
; __device__ __forceinline__ void gemm_phase(PG8_LAS unsigned char* lds, const Gemm g, const Sched& S, const Epi& E, const int tid_in) {
;     ...
;         float rsv[8]; E.pre(cur, wr, fr, rsv);
;         const bool has_next = S.next(ui + 1, nxt);
;         const char* nA = has_next ? (const char*)g.A + (size_t)nxt.pm * tstep : cA; const char* nB = has_next ? (const char*)g.Bt + (size_t)nxt.pn * tstep : cB;
;         for (int t = 0; t < nt; t += 2) {
;             const bool last = (t == nt - 2);
;             const char* a1 = cA + (size_t)(t + 1) * kstep;
;             const char* a2 = last ? nA : cA + (size_t)(t + 2) * kstep; const char* b2 = last ? nB : cB + (size_t)(t + 2) * kstep;
;             const char* a3 = a2 + kstep; const char* b3 = b2 + kstep;
;             if (last && has_next) S.a_ready(nxt);
;     ...
; #pragma unroll
;         for (int a = 0; a < 2; ++a)
; #pragma unroll
;             for (int b = 0; b < 2; ++b)
; #pragma unroll
;                 for (int m = 0; m < 4; ++m)
; #pragma unroll
;                     for (int n = 0; n < 2; ++n) acc[a][b][m][n] = (f32x4){0.f, 0.f, 0.f, 0.f};
;         cur = nxt; cA = nA; cB = nB; ++ui;
.LBB0_91:
	s_ashr_i32 s11, s10, 31
	s_lshl_b64 s[42:43], s[10:11], 19
	s_add_u32 s72, s1, s42
	s_addc_u32 s73, s2, s43
	s_and_b64 s[42:43], s[4:5], exec
	s_cselect_b32 s11, s73, s7
	s_cselect_b32 s42, s72, s6
	s_ashr_i32 s71, s70, 31
	s_lshl_b64 s[58:59], s[70:71], 19
	s_add_u32 s74, s3, s58
	s_addc_u32 s75, s20, s59
	s_and_b64 s[58:59], s[4:5], exec
	s_cselect_b32 s43, s75, s79
	s_cselect_b32 s58, s74, s78
	s_add_u32 s6, s6, 0x40080
	s_addc_u32 s7, s7, 0
	s_add_u32 s59, s78, 0x100
	v_mov_b32_e32 v2, 0
	s_addc_u32 s60, s79, 0
	s_mov_b32 s61, -2
	v_mov_b32_e32 v3, v2
	v_mov_b64_e32 v[4:5], 0
	v_mov_b64_e32 v[6:7], 0
	v_mov_b64_e32 v[8:9], 0
	v_mov_b64_e32 v[18:19], 0
	v_mov_b64_e32 v[20:21], 0
	v_mov_b64_e32 v[22:23], 0
	v_mov_b64_e32 v[24:25], 0
	v_mov_b64_e32 v[34:35], 0
	v_mov_b64_e32 v[36:37], 0
	v_mov_b64_e32 v[38:39], 0
	v_mov_b64_e32 v[40:41], 0
	v_mov_b64_e32 v[50:51], 0
	v_mov_b64_e32 v[52:53], 0
	v_mov_b64_e32 v[54:55], 0
	v_mov_b64_e32 v[56:57], 0
	v_mov_b64_e32 v[10:11], 0
	s_waitcnt lgkmcnt(0)
	v_mov_b64_e32 v[12:13], 0
	v_mov_b64_e32 v[14:15], 0
	v_mov_b64_e32 v[16:17], 0
	v_mov_b64_e32 v[26:27], 0
	v_mov_b64_e32 v[28:29], 0
	v_mov_b64_e32 v[30:31], 0
	v_mov_b64_e32 v[32:33], 0
	v_mov_b64_e32 v[42:43], 0
	v_mov_b64_e32 v[44:45], 0
	v_mov_b64_e32 v[46:47], 0
	v_mov_b64_e32 v[48:49], 0
	v_mov_b64_e32 v[58:59], 0
	v_mov_b64_e32 v[60:61], 0
	v_mov_b64_e32 v[62:63], 0
	v_mov_b64_e32 v[64:65], 0
	v_mov_b64_e32 v[66:67], 0
	v_mov_b64_e32 v[68:69], 0
	v_mov_b64_e32 v[70:71], 0
	v_mov_b64_e32 v[72:73], 0
	v_mov_b64_e32 v[82:83], 0
	v_mov_b64_e32 v[84:85], 0
	v_mov_b64_e32 v[86:87], 0
	v_mov_b64_e32 v[88:89], 0
	v_mov_b64_e32 v[98:99], 0
	v_mov_b64_e32 v[100:101], 0
	v_mov_b64_e32 v[102:103], 0
	v_mov_b64_e32 v[104:105], 0
	v_mov_b64_e32 v[114:115], 0
	v_mov_b64_e32 v[116:117], 0
	v_mov_b64_e32 v[118:119], 0
	v_mov_b64_e32 v[120:121], 0
	v_mov_b64_e32 v[74:75], 0
	v_mov_b64_e32 v[76:77], 0
	v_mov_b64_e32 v[78:79], 0
	v_mov_b64_e32 v[80:81], 0
	v_mov_b64_e32 v[90:91], 0
	v_mov_b64_e32 v[92:93], 0
	v_mov_b64_e32 v[94:95], 0
	v_mov_b64_e32 v[96:97], 0
	v_mov_b64_e32 v[106:107], 0
	v_mov_b64_e32 v[108:109], 0
	v_mov_b64_e32 v[110:111], 0
	v_mov_b64_e32 v[112:113], 0
	v_mov_b64_e32 v[122:123], 0
	v_mov_b64_e32 v[124:125], 0
	v_mov_b64_e32 v[126:127], 0
	v_mov_b64_e32 v[128:129], 0
	.p2alignl 6, 3212836864
	s_nop 0

; #define WAIT_BAR(N) asm volatile("s_waitcnt vmcnt(" #N ") lgkmcnt(0)\n\ts_barrier":::"memory")
;   #define DMA_K(t,slot) glds16(ksrc+(long)(t)*KVBLK*DMI,(unsigned)__builtin_amdgcn_readfirstlane(kdst+(slot)))
;   #define DMA_V(t,slot) glds16(vsrc+(long)(t)*KVBLK*DMI,(unsigned)__builtin_amdgcn_readfirstlane(vdst+(slot)))
;   #define BIASADD(P0,P1,t) do{ if(BIAS){ const lds_fptr bp_=biasl+KVBLK*(t); _Pragma("unroll") for(int i_=0;i_<4;++i_){ \
;       const f32x4_t b0_=*(const __attribute__((address_space(3))) f32x4_t*)(bp_+8*i_), b1_=*(const __attribute__((address_space(3))) f32x4_t*)(bp_+32+8*i_); \
;       _Pragma("unroll") for(int j_=0;j_<4;++j_){ P0[4*i_+j_]+=b0_[j_]; P1[4*i_+j_]+=b1_[j_]; } } } }while(0)
;   #define CMASK(P0,P1,t) do{int jb_=(t)-(NT-4); if(jb_>=0)cmask(P0,P1,jb_,qrel,hi);}while(0)
;   #define START(P0,P1) do{ const float rm=rowmax(P0,P1); resc=false; \
;     { const float dl=rm; mhat=fadd_s(mhat,dl); \
;       _Pragma("unroll") for(int r=0;r<16;++r){P0[r]=fsub_s(P0[r],dl);P1[r]=fsub_s(P1[r],dl);} \
;       _Pragma("unroll") for(int r=0;r<16;++r)negm[r]=-mhat; asm volatile("":"+v"(negm)); } \
;     _Pragma("unroll") for(int r=0;r<16;++r)P0[r]=__builtin_amdgcn_exp2f(P0[r]); }while(0)
;   #define ROT() do{sl_prev=sl_cur;sl_cur=sl_next;sl_next=(sl_next==(NSLOT-1)*SLOTB)?0:sl_next+SLOTB;}while(0)
;   #define CMASK(P0,P1,t) do{}while(0)
;   #define CMASK(P0,P1,t) do{int jb_=(t)-(NT-4); if(jb_>=0)cmask(P0,P1,jb_,qrel,hi);}while(0)
; #define WAIT_BAR(N) asm volatile("s_waitcnt vmcnt(" #N ") lgkmcnt(0)\n\ts_barrier":::"memory")
;   #define CMASK(P0,P1,t) do{}while(0)
; template<int THRL,bool BIAS> __device__ __forceinline__ void attn_unit(int b,int qb,const bf16*Q,const bf16*__restrict__ K,const bf16*__restrict__ V,bf16*O,const float*__restrict__ biasg,char*shm,const int tid_in){
;     ...
;   f32x16 pA0,pA1,pB0,pB1;
;   int sl_prev=0,sl_cur=0,sl_next=SLOTB;
;     ...
;   DMA_K(2,2*SLOTB);
;   WAIT_BAR(3);
;   qkt(pA0,pA1,Kbase,qr,negm,r32,hi);asm volatile("s_nop 15\n\ts_nop 7":"+v"(pA0),"+v"(pA1));BIASADD(pA0,pA1,0);CMASK(pA0,pA1,0);
;   START(pA0,pA1);
;   _Pragma("unroll") for(int r=0;r<16;++r)pA1[r]=__builtin_amdgcn_exp2f(pA1[r]);
;   WAIT_BAR(0);
;   DMA_K(3,0);DMA_V(1,SLOTB);
;   ROT();
;   kload8(kf,kp0+sl_cur);
;   WAIT_BAR(2);
;   s16x4 vlo[8],vhi[8]; u32x4 pw0,pw1,pw2,pw3;
;     ...
;   int t=1;
;     ...
;   for(;t+5<NT;t+=2){
.LBB0_249:
	v_lshlrev_b32_e32 v0, 1, v42
	v_and_b32_e32 v235, 32, v0
	v_lshrrev_b32_e32 v0, 2, v42
	v_and_or_b32 v0, v0, 3, v221
	v_lshlrev_b32_e32 v222, 6, v0
	v_add_u32_e32 v0, 0, v235
	v_add3_u32 v225, v0, v220, v222
	v_max3_f32 v0, v40, v41, v2
	v_max3_f32 v12, v38, v39, v3
	s_and_b32 s5, s22, 0x3fffffc0
	v_max3_f32 v0, v0, v4, v5
	v_max3_f32 v12, v12, v34, v35
	s_lshl_b32 s5, s5, 2
	v_max3_f32 v0, v0, v36, v37
	v_max3_f32 v12, v12, v8, v9
	s_add_i32 s19, s5, 0
	v_max3_f32 v0, v0, v28, v29
	v_max3_f32 v12, v12, v22, v23
	s_cmp_lg_u32 0, -1
	v_max3_f32 v0, v0, v24, v25
	v_max3_f32 v12, v12, v10, v11
	s_mov_b32 s18, 1
	v_max3_f32 v0, v0, v26, v27
	v_max3_f32 v12, v12, v18, v19
	s_mov_b32 s7, 0
	v_max3_f32 v0, v0, v20, v21
	v_max3_f32 v12, v12, v6, v7
	v_lshl_add_u32 v237, v233, 2, s19
	v_max3_f32 v0, v0, v14, v15
	v_lshl_add_u32 v234, v221, 2, s19
	v_max_f32_e32 v0, v0, v12
	s_nop 0
	v_mov_b32_e32 v12, v0
	s_nop 1
	v_permlane32_swap_b32_e32 v0, v12
	v_max_f32_e32 v0, v0, v12
	s_nop 0
	v_add_f32_e32 v224, v1, v0
	v_sub_f32_e32 v2, v2, v0
	v_sub_f32_e32 v3, v3, v0
	v_sub_f32_e32 v12, v40, v0
	v_sub_f32_e32 v13, v41, v0
	v_sub_f32_e32 v16, v38, v0
	s_nop 0
	v_xor_b32_e32 v48, 0x80000000, v224
	v_mov_b32_e32 v49, v48
	v_mov_b32_e32 v50, v48
	v_mov_b32_e32 v51, v48
	v_mov_b32_e32 v52, v48
	v_mov_b32_e32 v53, v48
	v_mov_b32_e32 v54, v48
	v_mov_b32_e32 v55, v48
	v_mov_b32_e32 v56, v48
	v_mov_b32_e32 v57, v48
	v_mov_b32_e32 v58, v48
	v_mov_b32_e32 v59, v48
	v_mov_b32_e32 v60, v48
	v_mov_b32_e32 v61, v48
	v_mov_b32_e32 v62, v48
	v_mov_b32_e32 v63, v48
	s_waitcnt vmcnt(0) lgkmcnt(0)
	s_barrier
	v_exp_f32_e32 v64, v2
	v_exp_f32_e32 v65, v3
	v_lshl_add_u64 v[2:3], v[212:213], 0, s[50:51]
	s_mov_b32 s5, m0
	s_mov_b32 m0, s38
	s_nop 0
	global_load_lds_dwordx4 v[2:3], off
	s_mov_b32 m0, s5
	s_cselect_b32 s5, 0, 0
	s_add_i32 s4, s5, s4
	v_lshl_add_u64 v[2:3], v[214:215], 0, s[46:47]
	s_add_i32 s4, s4, 0x8000
	s_mov_b32 s5, m0
	s_mov_b32 m0, s4
	s_nop 0
	global_load_lds_dwordx4 v[2:3], off
	s_mov_b32 m0, s5
	ds_read_b128 v[188:191], v238 offset:8192
	ds_read_b128 v[184:187], v238 offset:8704
	ds_read_b128 v[180:183], v238 offset:10240
	ds_read_b128 v[176:179], v238 offset:10752
	ds_read_b128 v[172:175], v238 offset:12288
	ds_read_b128 v[168:171], v238 offset:12800
	ds_read_b128 v[164:167], v238 offset:14336
	ds_read_b128 v[160:163], v238 offset:14848
	v_sub_f32_e32 v4, v4, v0
	v_sub_f32_e32 v17, v39, v0
	v_sub_f32_e32 v5, v5, v0
	v_sub_f32_e32 v30, v36, v0
	v_sub_f32_e32 v28, v28, v0
	v_sub_f32_e32 v31, v37, v0
	v_sub_f32_e32 v29, v29, v0
	v_sub_f32_e32 v32, v34, v0
	v_sub_f32_e32 v8, v8, v0
	v_sub_f32_e32 v33, v35, v0
	v_sub_f32_e32 v9, v9, v0
	v_sub_f32_e32 v24, v24, v0
	v_sub_f32_e32 v26, v26, v0
	v_sub_f32_e32 v25, v25, v0
	v_sub_f32_e32 v27, v27, v0
	v_sub_f32_e32 v22, v22, v0
	v_sub_f32_e32 v10, v10, v0
	v_sub_f32_e32 v23, v23, v0
	v_sub_f32_e32 v11, v11, v0
	v_sub_f32_e32 v20, v20, v0
	v_sub_f32_e32 v14, v14, v0
	v_sub_f32_e32 v21, v21, v0
	v_sub_f32_e32 v15, v15, v0
	v_sub_f32_e32 v18, v18, v0
	v_sub_f32_e32 v6, v6, v0
	v_sub_f32_e32 v19, v19, v0
	v_sub_f32_e32 v0, v7, v0
	v_exp_f32_e32 v80, v12
	v_exp_f32_e32 v81, v13
	v_exp_f32_e32 v82, v16
	v_exp_f32_e32 v83, v17
	v_exp_f32_e32 v84, v30
	v_exp_f32_e32 v85, v31
	v_exp_f32_e32 v86, v32
	v_exp_f32_e32 v87, v33
	v_exp_f32_e32 v88, v24
	v_exp_f32_e32 v89, v25
	v_exp_f32_e32 v90, v22
	v_exp_f32_e32 v91, v23
	v_exp_f32_e32 v92, v20
	v_exp_f32_e32 v93, v21
	v_exp_f32_e32 v94, v18
	v_exp_f32_e32 v95, v19
	v_exp_f32_e32 v66, v4
	v_exp_f32_e32 v67, v5
	v_exp_f32_e32 v68, v28
	v_exp_f32_e32 v69, v29
	v_exp_f32_e32 v70, v8
	v_exp_f32_e32 v71, v9
	v_exp_f32_e32 v72, v26
	v_exp_f32_e32 v73, v27
	v_exp_f32_e32 v74, v10
	v_exp_f32_e32 v75, v11
	v_exp_f32_e32 v76, v14
	v_exp_f32_e32 v77, v15
	v_exp_f32_e32 v78, v6
	v_exp_f32_e32 v79, v0
	s_waitcnt vmcnt(2) lgkmcnt(0)
	s_barrier
	s_cmp_lt_i32 s35, 7
	v_cmp_gt_u32_e64 s[4:5], 32, v231
	s_cbranch_scc1 .LBB0_265
	v_mov_b32_e32 v14, v1
	v_mov_b32_e32 v15, v1
	v_readlane_b32 s7, v255, 10
	v_mov_b32_e32 v0, v1
	v_mov_b32_e32 v2, v1
	v_mov_b32_e32 v3, v1
	v_mov_b32_e32 v4, v1
	v_mov_b32_e32 v5, v1
	v_mov_b32_e32 v6, v1
	v_mov_b32_e32 v7, v1
	v_mov_b32_e32 v8, v1
	v_mov_b32_e32 v9, v1
	v_mov_b32_e32 v10, v1
	v_mov_b32_e32 v11, v1
	v_mov_b32_e32 v12, v1
	v_mov_b32_e32 v13, v1
	v_mov_b64_e32 v[46:47], v[14:15]
	v_mov_b64_e32 v[30:31], v[14:15]
	v_lshl_add_u64 v[200:201], v[214:215], 0, s[50:51]
	v_lshl_add_u64 v[202:203], v[212:213], 0, s[52:53]
	v_lshl_add_u32 v204, v239, 4, s7
	s_mov_b32 s18, 0
	s_movk_i32 s7, 0x4000
	s_movk_i32 s69, 0x2000
	v_mov_b32_e32 v230, 0
	s_mov_b32 s68, 6
	v_mov_b64_e32 v[44:45], v[12:13]
	v_mov_b64_e32 v[42:43], v[10:11]
	v_mov_b64_e32 v[40:41], v[8:9]
	v_mov_b64_e32 v[38:39], v[6:7]
	v_mov_b64_e32 v[36:37], v[4:5]
	v_mov_b64_e32 v[34:35], v[2:3]
	v_mov_b64_e32 v[32:33], v[0:1]
	v_mov_b64_e32 v[28:29], v[12:13]
	v_mov_b64_e32 v[26:27], v[10:11]
	v_mov_b64_e32 v[24:25], v[8:9]
	v_mov_b64_e32 v[22:23], v[6:7]
	v_mov_b64_e32 v[20:21], v[4:5]
	v_mov_b64_e32 v[18:19], v[2:3]
	v_mov_b64_e32 v[16:17], v[0:1]
	.p2alignl 6, 3212836864
	s_nop 0

; #define WAIT_BAR(N) asm volatile("s_waitcnt vmcnt(" #N ") lgkmcnt(0)\n\ts_barrier":::"memory")
;   #define DMA_K(t,slot) glds16(ksrc+(long)(t)*KVBLK*DMI,(unsigned)__builtin_amdgcn_readfirstlane(kdst+(slot)))
;   #define DMA_V(t,slot) glds16(vsrc+(long)(t)*KVBLK*DMI,(unsigned)__builtin_amdgcn_readfirstlane(vdst+(slot)))
;   #define BIASADD(P0,P1,t) do{ if(BIAS){ const lds_fptr bp_=biasl+KVBLK*(t); _Pragma("unroll") for(int i_=0;i_<4;++i_){ \
;       const f32x4_t b0_=*(const __attribute__((address_space(3))) f32x4_t*)(bp_+8*i_), b1_=*(const __attribute__((address_space(3))) f32x4_t*)(bp_+32+8*i_); \
;       _Pragma("unroll") for(int j_=0;j_<4;++j_){ P0[4*i_+j_]+=b0_[j_]; P1[4*i_+j_]+=b1_[j_]; } } } }while(0)
;   #define CMASK(P0,P1,t) do{int jb_=(t)-(NT-4); if(jb_>=0)cmask(P0,P1,jb_,qrel,hi);}while(0)
;   #define START(P0,P1) do{ const float rm=rowmax(P0,P1); resc=false; \
;     { const float dl=rm; mhat=fadd_s(mhat,dl); \
;       _Pragma("unroll") for(int r=0;r<16;++r){P0[r]=fsub_s(P0[r],dl);P1[r]=fsub_s(P1[r],dl);} \
;       _Pragma("unroll") for(int r=0;r<16;++r)negm[r]=-mhat; asm volatile("":"+v"(negm)); } \
;     _Pragma("unroll") for(int r=0;r<16;++r)P0[r]=__builtin_amdgcn_exp2f(P0[r]); }while(0)
;   #define ROT() do{sl_prev=sl_cur;sl_cur=sl_next;sl_next=(sl_next==(NSLOT-1)*SLOTB)?0:sl_next+SLOTB;}while(0)
;   #define CMASK(P0,P1,t) do{}while(0)
;   #define CMASK(P0,P1,t) do{int jb_=(t)-(NT-4); if(jb_>=0)cmask(P0,P1,jb_,qrel,hi);}while(0)
;   #define CMASK(P0,P1,t) do{int jb_=(t)-(NT-4); if(jb_>=0)cmask(P0,P1,jb_,qrel,hi);}while(0)
; template<int THRL,bool BIAS> __device__ __forceinline__ void attn_unit(int b,int qb,const bf16*Q,const bf16*__restrict__ K,const bf16*__restrict__ V,bf16*O,const float*__restrict__ biasg,char*shm,const int tid_in,const bool comb,const bf16*O0,const float lam,const float osc,const float*__restrict__ ...
;     ...
;   f32x16 pA0,pA1,pB0,pB1;
;   int sl_prev=0,sl_cur=0,sl_next=SLOTB;
;     ...
;   DMA_K(2,2*SLOTB);
;   WAIT_BAR(3);
;   qkt(pA0,pA1,Kbase,qr,negm,r32,hi);asm volatile("s_nop 15\n\ts_nop 7":"+v"(pA0),"+v"(pA1));BIASADD(pA0,pA1,0);CMASK(pA0,pA1,0);
;   START(pA0,pA1);
;   _Pragma("unroll") for(int r=0;r<16;++r)pA1[r]=__builtin_amdgcn_exp2f(pA1[r]);
;   WAIT_BAR(0);
;   DMA_K(3,0);DMA_V(1,SLOTB);
;   ROT();
;   kload8(kf,kp0+sl_cur);
;   WAIT_BAR(3);
;   s16x4 vlo[3],vhi[3]; u32x4 pw0,pw1,pw2,pw3;
;     ...
;   int t=1;
;     ...
;   for(;t+5<NT;t+=2){
.LBB0_278:
	v_lshlrev_b32_e32 v0, 1, v34
	v_and_b32_e32 v248, 32, v0
	v_lshlrev_b32_e32 v0, 4, v34
	v_and_b32_e32 v0, 0xc0, v0
	v_lshl_or_b32 v240, v232, 8, v0
	v_add_u32_e32 v0, 0, v248
	v_add3_u32 v245, v0, v242, v240
	v_max3_f32 v0, v18, v19, v2
	v_max3_f32 v34, v20, v21, v3
	s_and_b32 s5, s5, 0x3fffffc0
	v_max3_f32 v0, v0, v4, v5
	v_max3_f32 v34, v34, v24, v25
	s_lshl_b32 s5, s5, 2
	v_max3_f32 v0, v0, v22, v23
	v_max3_f32 v34, v34, v8, v9
	s_add_i32 s62, s5, 0
	v_max3_f32 v0, v0, v6, v7
	v_max3_f32 v34, v34, v28, v29
	s_add_i32 s62, s62, 0x12000
	v_max3_f32 v0, v0, v26, v27
	v_max3_f32 v34, v34, v12, v13
	s_cmp_lg_u32 0, -1
	v_max3_f32 v0, v0, v10, v11
	v_max3_f32 v34, v34, v32, v33
	s_mov_b32 s6, 1
	v_max3_f32 v0, v0, v30, v31
	v_max3_f32 v34, v34, v16, v17
	s_mov_b32 s76, 0
	v_max3_f32 v0, v0, v14, v15
	v_lshlrev_b32_e32 v230, 4, v232
	v_max_f32_e32 v0, v0, v34
	v_lshl_add_u32 v241, v252, 2, s62
	v_mov_b32_e32 v34, v0
	s_nop 1
	v_permlane32_swap_b32_e32 v0, v34
	v_max_f32_e32 v0, v0, v34
	s_nop 0
	v_add_f32_e32 v224, v1, v0
	v_sub_f32_e32 v2, v2, v0
	v_sub_f32_e32 v3, v3, v0
	v_sub_f32_e32 v18, v18, v0
	v_sub_f32_e32 v19, v19, v0
	v_sub_f32_e32 v20, v20, v0
	s_nop 0
	v_xor_b32_e32 v80, 0x80000000, v224
	v_mov_b32_e32 v81, v80
	v_mov_b32_e32 v82, v80
	v_mov_b32_e32 v83, v80
	v_mov_b32_e32 v84, v80
	v_mov_b32_e32 v85, v80
	v_mov_b32_e32 v86, v80
	v_mov_b32_e32 v87, v80
	v_mov_b32_e32 v88, v80
	v_mov_b32_e32 v89, v80
	v_mov_b32_e32 v90, v80
	v_mov_b32_e32 v91, v80
	v_mov_b32_e32 v92, v80
	v_mov_b32_e32 v93, v80
	v_mov_b32_e32 v94, v80
	v_mov_b32_e32 v95, v80
	s_waitcnt vmcnt(0) lgkmcnt(0)
	s_barrier
	v_exp_f32_e32 v96, v2
	v_exp_f32_e32 v97, v3
	v_lshl_add_u64 v[2:3], v[234:235], 0, s[50:51]
	s_mov_b32 s5, m0
	s_mov_b32 m0, s64
	s_nop 0
	global_load_lds_dwordx4 v[2:3], off
	s_mov_b32 m0, s5
	s_cselect_b32 s5, 0, 0
	s_add_i32 s7, s5, s4
	v_lshl_add_u64 v[2:3], v[236:237], 0, s[46:47]
	s_add_i32 s4, s7, 0xa000
	s_mov_b32 s5, m0
	s_mov_b32 m0, s4
	s_nop 0
	global_load_lds_dwordx4 v[2:3], off
	s_mov_b32 m0, s5
	s_mov_b64 s[4:5], 0x60080
	v_lshl_add_u64 v[2:3], v[236:237], 0, s[4:5]
	s_add_i32 s7, s7, 0xc000
	s_mov_b32 s4, m0
	s_mov_b32 m0, s7
	s_nop 0
	global_load_lds_dwordx4 v[2:3], off
	s_mov_b32 m0, s4
	ds_read_b128 v[220:223], v225 offset:8192
	ds_read_b128 v[212:215], v225 offset:8704
	ds_read_b128 v[216:219], v225 offset:10240
	ds_read_b128 v[204:207], v225 offset:10752
	ds_read_b128 v[208:211], v225 offset:12288
	ds_read_b128 v[200:203], v225 offset:12800
	ds_read_b128 v[196:199], v225 offset:14336
	ds_read_b128 v[192:195], v225 offset:14848
	v_sub_f32_e32 v4, v4, v0
	v_sub_f32_e32 v21, v21, v0
	v_sub_f32_e32 v5, v5, v0
	v_sub_f32_e32 v22, v22, v0
	v_sub_f32_e32 v6, v6, v0
	v_sub_f32_e32 v23, v23, v0
	v_sub_f32_e32 v7, v7, v0
	v_sub_f32_e32 v24, v24, v0
	v_sub_f32_e32 v8, v8, v0
	v_sub_f32_e32 v25, v25, v0
	v_sub_f32_e32 v9, v9, v0
	v_sub_f32_e32 v26, v26, v0
	v_sub_f32_e32 v10, v10, v0
	v_sub_f32_e32 v27, v27, v0
	v_sub_f32_e32 v11, v11, v0
	v_sub_f32_e32 v28, v28, v0
	v_sub_f32_e32 v12, v12, v0
	v_sub_f32_e32 v29, v29, v0
	v_sub_f32_e32 v13, v13, v0
	v_sub_f32_e32 v30, v30, v0
	v_sub_f32_e32 v14, v14, v0
	v_sub_f32_e32 v31, v31, v0
	v_sub_f32_e32 v15, v15, v0
	v_sub_f32_e32 v32, v32, v0
	v_sub_f32_e32 v16, v16, v0
	v_sub_f32_e32 v33, v33, v0
	v_sub_f32_e32 v0, v17, v0
	v_exp_f32_e32 v112, v18
	v_exp_f32_e32 v113, v19
	v_exp_f32_e32 v114, v20
	v_exp_f32_e32 v115, v21
	v_exp_f32_e32 v116, v22
	v_exp_f32_e32 v117, v23
	v_exp_f32_e32 v118, v24
	v_exp_f32_e32 v119, v25
	v_exp_f32_e32 v120, v26
	v_exp_f32_e32 v121, v27
	v_exp_f32_e32 v122, v28
	v_exp_f32_e32 v123, v29
	v_exp_f32_e32 v124, v30
	v_exp_f32_e32 v125, v31
	v_exp_f32_e32 v126, v32
	v_exp_f32_e32 v127, v33
	v_exp_f32_e32 v98, v4
	v_exp_f32_e32 v99, v5
	v_exp_f32_e32 v100, v6
	v_exp_f32_e32 v101, v7
	v_exp_f32_e32 v102, v8
	v_exp_f32_e32 v103, v9
	v_exp_f32_e32 v104, v10
	v_exp_f32_e32 v105, v11
	v_exp_f32_e32 v106, v12
	v_exp_f32_e32 v107, v13
	v_exp_f32_e32 v108, v14
	v_exp_f32_e32 v109, v15
	v_exp_f32_e32 v110, v16
	v_exp_f32_e32 v111, v0
	s_waitcnt vmcnt(3) lgkmcnt(0)
	s_barrier
	s_andn2_b64 vcc, exec, s[22:23]
	v_cmp_gt_u32_e64 s[4:5], 32, v253
	s_cbranch_vccnz .LBB0_294
	v_mov_b32_e32 v14, v1
	v_mov_b32_e32 v15, v1
	v_mov_b32_e32 v0, v1
	v_mov_b32_e32 v2, v1
	v_mov_b32_e32 v3, v1
	v_mov_b32_e32 v4, v1
	v_mov_b32_e32 v5, v1
	v_mov_b32_e32 v6, v1
	v_mov_b32_e32 v7, v1
	v_mov_b32_e32 v8, v1
	v_mov_b32_e32 v9, v1
	v_mov_b32_e32 v10, v1
	v_mov_b32_e32 v11, v1
	v_mov_b32_e32 v12, v1
	v_mov_b32_e32 v13, v1
	v_mov_b64_e32 v[78:79], v[14:15]
	v_mov_b64_e32 v[62:63], v[14:15]
	v_mov_b64_e32 v[46:47], v[14:15]
	v_mov_b64_e32 v[30:31], v[14:15]
	s_mov_b32 s72, 0
	s_movk_i32 s76, 0x4000
	s_movk_i32 s78, 0x2000
	v_mov_b32_e32 v231, 0
	s_mov_b32 s77, 6
	s_mov_b64 s[6:7], 0
	v_mov_b64_e32 v[76:77], v[12:13]
	v_mov_b64_e32 v[74:75], v[10:11]
	v_mov_b64_e32 v[72:73], v[8:9]
	v_mov_b64_e32 v[70:71], v[6:7]
	v_mov_b64_e32 v[68:69], v[4:5]
	v_mov_b64_e32 v[66:67], v[2:3]
	v_mov_b64_e32 v[64:65], v[0:1]
	v_mov_b64_e32 v[60:61], v[12:13]
	v_mov_b64_e32 v[58:59], v[10:11]
	v_mov_b64_e32 v[56:57], v[8:9]
	v_mov_b64_e32 v[54:55], v[6:7]
	v_mov_b64_e32 v[52:53], v[4:5]
	v_mov_b64_e32 v[50:51], v[2:3]
	v_mov_b64_e32 v[48:49], v[0:1]
	v_mov_b64_e32 v[44:45], v[12:13]
	v_mov_b64_e32 v[42:43], v[10:11]
	v_mov_b64_e32 v[40:41], v[8:9]
	v_mov_b64_e32 v[38:39], v[6:7]
	v_mov_b64_e32 v[36:37], v[4:5]
	v_mov_b64_e32 v[34:35], v[2:3]
	v_mov_b64_e32 v[32:33], v[0:1]
	v_mov_b64_e32 v[28:29], v[12:13]
	v_mov_b64_e32 v[26:27], v[10:11]
	v_mov_b64_e32 v[24:25], v[8:9]
	v_mov_b64_e32 v[22:23], v[6:7]
	v_mov_b64_e32 v[20:21], v[4:5]
	v_mov_b64_e32 v[18:19], v[2:3]
	v_mov_b64_e32 v[16:17], v[0:1]
	.p2alignl 6, 3212836864
	s_nop 0

; template <class Epi, class Sched, bool ALIGN_EPI = false, bool SP2 = false>
; __device__ __forceinline__ void gemm_phase(PG8_LAS unsigned char* lds, const Gemm g, const Sched& S, const Epi& E, const int tid_in) {
;     ...
;         float rsv[8]; E.pre(cur, wr, fr, rsv);
;         const bool has_next = S.next(ui + 1, nxt);
;         const char* nA = has_next ? (const char*)g.A + (size_t)nxt.pm * tstep : cA; const char* nB = has_next ? (const char*)g.Bt + (size_t)nxt.pn * tstep : cB;
;         for (int t = 0; t < nt; t += 2) {
;             const bool last = (t == nt - 2);
;             const char* a1 = cA + (size_t)(t + 1) * kstep;
;             const char* a2 = last ? nA : cA + (size_t)(t + 2) * kstep; const char* b2 = last ? nB : cB + (size_t)(t + 2) * kstep;
;             const char* a3 = a2 + kstep; const char* b3 = b2 + kstep;
;             if (last && has_next) S.a_ready(nxt);
;     ...
; #pragma unroll
;         for (int a = 0; a < 2; ++a)
; #pragma unroll
;             for (int b = 0; b < 2; ++b)
; #pragma unroll
;                 for (int m = 0; m < 4; ++m)
; #pragma unroll
;                     for (int n = 0; n < 2; ++n) acc[a][b][m][n] = (f32x4){0.f, 0.f, 0.f, 0.f};
;         cur = nxt; cA = nA; cB = nB; ++ui;
.LBB0_484:
	s_ashr_i32 s15, s14, 31
	s_lshl_b64 s[18:19], s[14:15], 19
	s_add_u32 s18, s2, s18
	s_addc_u32 s19, s3, s19
	s_and_b64 s[22:23], s[4:5], exec
	s_cselect_b32 s15, s19, s69
	s_cselect_b32 s42, s18, s68
	s_ashr_i32 s13, s12, 31
	s_lshl_b64 s[22:23], s[12:13], 19
	s_add_u32 s22, s20, s22
	s_addc_u32 s23, s21, s23
	s_and_b64 s[58:59], s[4:5], exec
	s_cselect_b32 s13, s23, s71
	s_cselect_b32 s43, s22, s70
	s_add_u32 s68, s68, 0x40080
	s_addc_u32 s69, s69, 0
	s_add_u32 s58, s70, 0x100
	v_mov_b32_e32 v2, 0
	s_addc_u32 s59, s71, 0
	s_mov_b32 s60, -2
	v_mov_b32_e32 v3, v2
	v_mov_b64_e32 v[4:5], 0
	v_mov_b64_e32 v[6:7], 0
	v_mov_b64_e32 v[8:9], 0
	v_mov_b64_e32 v[10:11], 0
	v_mov_b64_e32 v[12:13], 0
	v_mov_b64_e32 v[18:19], 0
	v_mov_b64_e32 v[20:21], 0
	v_mov_b64_e32 v[26:27], 0
	v_mov_b64_e32 v[28:29], 0
	v_mov_b64_e32 v[34:35], 0
	v_mov_b64_e32 v[36:37], 0
	v_mov_b64_e32 v[42:43], 0
	v_mov_b64_e32 v[44:45], 0
	v_mov_b64_e32 v[50:51], 0
	v_mov_b64_e32 v[52:53], 0
	v_mov_b64_e32 v[14:15], 0
	v_mov_b64_e32 v[16:17], 0
	v_mov_b64_e32 v[22:23], 0
	v_mov_b64_e32 v[24:25], 0
	v_mov_b64_e32 v[30:31], 0
	v_mov_b64_e32 v[32:33], 0
	v_mov_b64_e32 v[38:39], 0
	v_mov_b64_e32 v[40:41], 0
	v_mov_b64_e32 v[46:47], 0
	v_mov_b64_e32 v[48:49], 0
	v_mov_b64_e32 v[54:55], 0
	v_mov_b64_e32 v[56:57], 0
	v_mov_b64_e32 v[58:59], 0
	v_mov_b64_e32 v[60:61], 0
	v_mov_b64_e32 v[62:63], 0
	v_mov_b64_e32 v[64:65], 0
	v_mov_b64_e32 v[66:67], 0
	v_mov_b64_e32 v[68:69], 0
	v_mov_b64_e32 v[70:71], 0
	v_mov_b64_e32 v[72:73], 0
	v_mov_b64_e32 v[74:75], 0
	v_mov_b64_e32 v[76:77], 0
	v_mov_b64_e32 v[82:83], 0
	v_mov_b64_e32 v[84:85], 0
	v_mov_b64_e32 v[90:91], 0
	v_mov_b64_e32 v[92:93], 0
	v_mov_b64_e32 v[98:99], 0
	v_mov_b64_e32 v[100:101], 0
	v_mov_b64_e32 v[106:107], 0
	v_mov_b64_e32 v[108:109], 0
	v_mov_b64_e32 v[114:115], 0
	v_mov_b64_e32 v[116:117], 0
	v_mov_b64_e32 v[78:79], 0
	v_mov_b64_e32 v[80:81], 0
	v_mov_b64_e32 v[86:87], 0
	v_mov_b64_e32 v[88:89], 0
	v_mov_b64_e32 v[94:95], 0
	v_mov_b64_e32 v[96:97], 0
	v_mov_b64_e32 v[102:103], 0
	v_mov_b64_e32 v[104:105], 0
	v_mov_b64_e32 v[110:111], 0
	v_mov_b64_e32 v[112:113], 0
	v_mov_b64_e32 v[118:119], 0
	v_mov_b64_e32 v[120:121], 0
	v_mov_b64_e32 v[122:123], 0
	v_mov_b64_e32 v[124:125], 0
	v_mov_b64_e32 v[126:127], 0
	v_mov_b64_e32 v[128:129], 0
	.p2alignl 6, 3212836864
	s_nop 0

; template <class Epi, class Sched, bool ALIGN_EPI = false, bool SP2 = false>
; __device__ __forceinline__ void gemm_phase(PG8_LAS unsigned char* lds, const Gemm g, const Sched& S, const Epi& E, const int tid_in) {
;     ...
;         float rsv[8]; E.pre(cur, wr, fr, rsv);
;         const bool has_next = S.next(ui + 1, nxt);
;         const char* nA = has_next ? (const char*)g.A + (size_t)nxt.pm * tstep : cA; const char* nB = has_next ? (const char*)g.Bt + (size_t)nxt.pn * tstep : cB;
;         for (int t = 0; t < nt; t += 2) {
;             const bool last = (t == nt - 2);
;             const char* a1 = cA + (size_t)(t + 1) * kstep;
;             const char* a2 = last ? nA : cA + (size_t)(t + 2) * kstep; const char* b2 = last ? nB : cB + (size_t)(t + 2) * kstep;
;             const char* a3 = a2 + kstep; const char* b3 = b2 + kstep;
;             if (last && has_next) S.a_ready(nxt);
;     ...
; #pragma unroll
;         for (int a = 0; a < 2; ++a)
; #pragma unroll
;             for (int b = 0; b < 2; ++b)
; #pragma unroll
;                 for (int m = 0; m < 4; ++m)
; #pragma unroll
;                     for (int n = 0; n < 2; ++n) acc[a][b][m][n] = (f32x4){0.f, 0.f, 0.f, 0.f};
;         cur = nxt; cA = nA; cB = nB; ++ui;
.LBB0_621:
	s_ashr_i32 s7, s6, 31
	s_lshl_b64 s[22:23], s[6:7], 19
	s_add_u32 s22, s1, s22
	s_addc_u32 s23, s2, s23
	s_and_b64 s[58:59], s[4:5], exec
	s_cselect_b32 s7, s23, s71
	s_cselect_b32 s43, s22, s70
	s_ashr_i32 s19, s18, 31
	s_lshl_b64 s[58:59], s[18:19], 19
	s_add_u32 s68, s3, s58
	s_addc_u32 s69, s20, s59
	s_and_b64 s[58:59], s[4:5], exec
	s_cselect_b32 s19, s69, s73
	s_cselect_b32 s58, s68, s72
	s_add_u32 s70, s70, 0x40080
	s_addc_u32 s71, s71, 0
	s_add_u32 s59, s72, 0x100
	v_mov_b32_e32 v2, 0
	s_addc_u32 s60, s73, 0
	s_mov_b32 s61, -2
	v_mov_b32_e32 v3, v2
	v_mov_b64_e32 v[4:5], 0
	v_mov_b64_e32 v[10:11], 0
	v_mov_b64_e32 v[12:13], 0
	v_mov_b64_e32 v[18:19], 0
	v_mov_b64_e32 v[20:21], 0
	v_mov_b64_e32 v[26:27], 0
	v_mov_b64_e32 v[28:29], 0
	v_mov_b64_e32 v[34:35], 0
	v_mov_b64_e32 v[36:37], 0
	v_mov_b64_e32 v[42:43], 0
	v_mov_b64_e32 v[44:45], 0
	v_mov_b64_e32 v[50:51], 0
	v_mov_b64_e32 v[52:53], 0
	v_mov_b64_e32 v[58:59], 0
	v_mov_b64_e32 v[60:61], 0
	v_mov_b64_e32 v[6:7], 0
	v_mov_b64_e32 v[8:9], 0
	v_mov_b64_e32 v[14:15], 0
	v_mov_b64_e32 v[16:17], 0
	v_mov_b64_e32 v[22:23], 0
	v_mov_b64_e32 v[24:25], 0
	v_mov_b64_e32 v[30:31], 0
	v_mov_b64_e32 v[32:33], 0
	v_mov_b64_e32 v[38:39], 0
	v_mov_b64_e32 v[40:41], 0
	v_mov_b64_e32 v[46:47], 0
	v_mov_b64_e32 v[48:49], 0
	v_mov_b64_e32 v[54:55], 0
	v_mov_b64_e32 v[56:57], 0
	v_mov_b64_e32 v[62:63], 0
	v_mov_b64_e32 v[64:65], 0
	v_mov_b64_e32 v[66:67], 0
	v_mov_b64_e32 v[68:69], 0
	v_mov_b64_e32 v[74:75], 0
	v_mov_b64_e32 v[76:77], 0
	v_mov_b64_e32 v[82:83], 0
	v_mov_b64_e32 v[84:85], 0
	v_mov_b64_e32 v[90:91], 0
	v_mov_b64_e32 v[92:93], 0
	v_mov_b64_e32 v[98:99], 0
	v_mov_b64_e32 v[100:101], 0
	v_mov_b64_e32 v[106:107], 0
	v_mov_b64_e32 v[108:109], 0
	v_mov_b64_e32 v[114:115], 0
	v_mov_b64_e32 v[116:117], 0
	v_mov_b64_e32 v[122:123], 0
	v_mov_b64_e32 v[124:125], 0
	v_mov_b64_e32 v[70:71], 0
	v_mov_b64_e32 v[72:73], 0
	v_mov_b64_e32 v[78:79], 0
	v_mov_b64_e32 v[80:81], 0
	v_mov_b64_e32 v[86:87], 0
	v_mov_b64_e32 v[88:89], 0
	v_mov_b64_e32 v[94:95], 0
	v_mov_b64_e32 v[96:97], 0
	v_mov_b64_e32 v[102:103], 0
	v_mov_b64_e32 v[104:105], 0
	v_mov_b64_e32 v[110:111], 0
	v_mov_b64_e32 v[112:113], 0
	v_mov_b64_e32 v[118:119], 0
	v_mov_b64_e32 v[120:121], 0
	v_mov_b64_e32 v[126:127], 0
	v_mov_b64_e32 v[128:129], 0
	.p2alignl 6, 3212836864
	s_nop 0

; template <class Epi, class Sched, bool ALIGN_EPI = false, bool SP2 = false>
; __device__ __forceinline__ void gemm_phase(PG8_LAS unsigned char* lds, const Gemm g, const Sched& S, const Epi& E, const int tid_in) {
;     ...
;         float rsv[8]; E.pre(cur, wr, fr, rsv);
;         const bool has_next = S.next(ui + 1, nxt);
;         const char* nA = has_next ? (const char*)g.A + (size_t)nxt.pm * tstep : cA; const char* nB = has_next ? (const char*)g.Bt + (size_t)nxt.pn * tstep : cB;
;         for (int t = 0; t < nt; t += 2) {
;             const bool last = (t == nt - 2);
;             const char* a1 = cA + (size_t)(t + 1) * kstep;
;             const char* a2 = last ? nA : cA + (size_t)(t + 2) * kstep; const char* b2 = last ? nB : cB + (size_t)(t + 2) * kstep;
;             const char* a3 = a2 + kstep; const char* b3 = b2 + kstep;
;             if (last && has_next) S.a_ready(nxt);
;     ...
; #pragma unroll
;         for (int a = 0; a < 2; ++a)
; #pragma unroll
;             for (int b = 0; b < 2; ++b)
; #pragma unroll
;                 for (int m = 0; m < 4; ++m)
; #pragma unroll
;                     for (int n = 0; n < 2; ++n) acc[a][b][m][n] = (f32x4){0.f, 0.f, 0.f, 0.f};
;         cur = nxt; cA = nA; cB = nB; ++ui;
.LBB0_702:
	s_add_u32 s62, s20, 0x100
	v_mov_b32_e32 v2, 0
	s_addc_u32 s63, s21, 0
	s_mov_b32 s64, -2
	v_mov_b32_e32 v3, v2
	v_mov_b64_e32 v[4:5], 0
	v_mov_b64_e32 v[6:7], 0
	v_mov_b64_e32 v[8:9], 0
	v_mov_b64_e32 v[10:11], 0
	v_mov_b64_e32 v[12:13], 0
	v_mov_b64_e32 v[18:19], 0
	v_mov_b64_e32 v[20:21], 0
	v_mov_b64_e32 v[26:27], 0
	v_mov_b64_e32 v[28:29], 0
	v_mov_b64_e32 v[34:35], 0
	v_mov_b64_e32 v[36:37], 0
	v_mov_b64_e32 v[42:43], 0
	v_mov_b64_e32 v[44:45], 0
	v_mov_b64_e32 v[50:51], 0
	v_mov_b64_e32 v[52:53], 0
	v_mov_b64_e32 v[14:15], 0
	v_mov_b64_e32 v[16:17], 0
	v_mov_b64_e32 v[22:23], 0
	v_mov_b64_e32 v[24:25], 0
	v_mov_b64_e32 v[30:31], 0
	v_mov_b64_e32 v[32:33], 0
	v_mov_b64_e32 v[38:39], 0
	v_mov_b64_e32 v[40:41], 0
	v_mov_b64_e32 v[46:47], 0
	v_mov_b64_e32 v[48:49], 0
	v_mov_b64_e32 v[54:55], 0
	v_mov_b64_e32 v[56:57], 0
	v_mov_b64_e32 v[58:59], 0
	v_mov_b64_e32 v[60:61], 0
	v_mov_b64_e32 v[62:63], 0
	v_mov_b64_e32 v[64:65], 0
	v_mov_b64_e32 v[66:67], 0
	v_mov_b64_e32 v[68:69], 0
	v_mov_b64_e32 v[70:71], 0
	v_mov_b64_e32 v[72:73], 0
	v_mov_b64_e32 v[74:75], 0
	v_mov_b64_e32 v[76:77], 0
	v_mov_b64_e32 v[82:83], 0
	v_mov_b64_e32 v[84:85], 0
	v_mov_b64_e32 v[90:91], 0
	v_mov_b64_e32 v[92:93], 0
	v_mov_b64_e32 v[98:99], 0
	v_mov_b64_e32 v[100:101], 0
	v_mov_b64_e32 v[106:107], 0
	v_mov_b64_e32 v[108:109], 0
	v_mov_b64_e32 v[114:115], 0
	v_mov_b64_e32 v[116:117], 0
	v_mov_b64_e32 v[78:79], 0
	v_mov_b64_e32 v[80:81], 0
	v_mov_b64_e32 v[86:87], 0
	v_mov_b64_e32 v[88:89], 0
	v_mov_b64_e32 v[94:95], 0
	v_mov_b64_e32 v[96:97], 0
	v_mov_b64_e32 v[102:103], 0
	v_mov_b64_e32 v[104:105], 0
	v_mov_b64_e32 v[110:111], 0
	v_mov_b64_e32 v[112:113], 0
	v_mov_b64_e32 v[118:119], 0
	v_mov_b64_e32 v[120:121], 0
	v_mov_b64_e32 v[122:123], 0
	v_mov_b64_e32 v[124:125], 0
	v_mov_b64_e32 v[126:127], 0
	v_mov_b64_e32 v[128:129], 0
	.p2alignl 6, 3212836864
	s_nop 0
